# DA attention: hand-written fast-path tile body with all LDS reads preloaded (counted lgkmcnt waits), max3 tree
# speedup vs baseline: 1.0354x; 1.0354x over previous
; #define FA_PREFETCH(kt_) do { int k0_ = (kt_) * 64; \
;     _Pragma("unroll") for (int i = 0; i < KPT; ++i) kreg[i] = __builtin_amdgcn_raw_buffer_load_b128(rsK, kvo[i], k0_ * k_stride * 2, 0); \
;     _Pragma("unroll") for (int i = 0; i < VPT; ++i) vreg[i] = __builtin_amdgcn_raw_buffer_load_b128(rsV, vvo[i], k0_ * 2, 0); } while (0)
; #define FA_PREFETCH_NEXT() do { \
;     _Pragma("unroll") for (int i = 0; i < KPT; ++i) kreg[i] = __builtin_amdgcn_raw_buffer_load_b128(rsNK, kvo[i], 0, 0); \
;     _Pragma("unroll") for (int i = 0; i < VPT; ++i) vreg[i] = __builtin_amdgcn_raw_buffer_load_b128(rsNV, vvo[i], 0, 0); } while (0)
; template <int NC, int DQK, int DV, bool CAUSAL, bool PF> ...
;     ...
;   for (int kt = 0; kt < nkt; ++kt) {
;     if (!PF) FA_PREFETCH(kt);
;     u16* Kb = Ks + (kt & 1) * KBUF; u16* Vb = Vs + (kt & 1) * VBUF;
;     _Pragma("unroll") for (int i = 0; i < KPT; ++i) { int id = tid + i * 512, row = id / KCH, cc = id % KCH; *(u32x4*)&Kb[row * KLD + cc * 8] = kreg[i]; }
;     _Pragma("unroll") for (int i = 0; i < VPT; ++i) {
;       int id = tid + i * 512, row = id >> 3, cc = id & 7;
;       int pos = 32 * (cc >> 2) + 16 * (cc & 1) + 4 * ((cc >> 1) & 1);
;       uint2 lo2, hi2; lo2.x = vreg[i][0]; lo2.y = vreg[i][1]; hi2.x = vreg[i][2]; hi2.y = vreg[i][3];
;       *(uint2*)&Vb[row * VLD + pos] = lo2; *(uint2*)&Vb[row * VLD + pos + 8] = hi2;
;     }
;     __syncthreads();
;     if (PF && kt + 1 < nkt) FA_PREFETCH(kt + 1); else if (PF && has_next_item) FA_PREFETCH_NEXT();
;     int k0 = kt * 64;
;     if (CAUSAL && k0 > qw0 + 15) continue;
;     bf16x8 pf[NC][2];
;     bool general = false; float bb = 0.f;
;     if (CAUSAL) { general = (qw0 - (k0 + 63)) < 113; bb = btab[127]; }
;     f32x4 bv[4];
;     if (general) {
;       bool diag = (k0 + 63) > qw0;
;       _Pragma("unroll") for (int m = 0; m < 4; ++m) _Pragma("unroll") for (int j = 0; j < 4; ++j) {
;         int dist = qpos - (k0 + 16 * m + fq * 4 + j);
;         int di = dist < 0 ? 0 : (dist > 127 ? 127 : dist);
;         float b = btab[di];
;         bv[m][j] = (diag && dist < 0) ? -1e30f : b;
;       }
;     }
.LBB0_1785:
	s_and_b32 s0, s34, 1
	s_mul_i32 s1, s0, 0x4400
	s_add_i32 s38, s1, 0
	v_add3_u32 v0, s38, v210, v204
	s_lshl_b32 s0, s0, 10
	s_waitcnt vmcnt(3)
	ds_write_b128 v0, v[34:37]
	v_add3_u32 v0, s38, v209, v205
	s_add_i32 s37, s38, s0
	s_waitcnt vmcnt(2)
	ds_write_b128 v0, v[38:41]
	v_lshl_add_u32 v0, v206, 1, s37
	v_add3_u32 v0, v0, v211, v212
	v_add_u32_e32 v1, v0, v208
	v_add_u32_e32 v0, v0, v207
	v_add_u32_e32 v1, 0x8800, v1
	v_add_u32_e32 v0, 0x8800, v0
	s_mov_b32 s14, s78
	s_mov_b32 s15, s79
	s_waitcnt vmcnt(0)
	ds_write2_b64 v1, v[42:43], v[44:45] offset1:2
	s_waitcnt vmcnt(0)
	ds_write2_b64 v0, v[46:47], v[48:49] offset1:2
	s_waitcnt lgkmcnt(0)
	s_barrier
	buffer_load_dwordx4 v[34:37], v198, s[76:79], s36 offen
	buffer_load_dwordx4 v[38:41], v199, s[76:79], s36 offen
	buffer_load_dwordx4 v[46:49], v200, s[12:15], s31 offen
	buffer_load_dwordx4 v[42:45], v201, s[12:15], s31 offen
	s_sub_i32 s0, s35, 63
	v_cmp_le_i32_e32 vcc, s0, v203
	s_and_saveexec_b64 s[0:1], vcc
	s_cbranch_execz .LBB0_1784
	v_readlane_b32 s6, v254, 39
	v_cmp_gt_i32_e32 vcc, s35, v202
	s_nop 0
	v_mov_b32_e32 v0, s6
	ds_read_b32 v170, v0
	v_cmp_le_i32_e64 s[6:7], s35, v202
	s_cbranch_vccz .Lda_fast
	s_and_saveexec_b64 s[14:15], vcc
	s_cbranch_execz .LBB0_1788
	v_add_u32_e32 v0, 51, v213
	v_cmp_gt_i32_e64 s[8:9], 0, v0
	v_med3_i32 v0, v0, 0, v184
	v_lshl_add_u32 v0, v0, 2, s91
	ds_read_b32 v0, v0
	v_cmp_gt_i32_e32 vcc, s35, v197
	s_and_b64 s[8:9], vcc, s[8:9]
	s_waitcnt lgkmcnt(0)
	v_cndmask_b32_e64 v122, v0, v185, s[8:9]
	v_add_u32_e32 v0, 50, v213
	v_cmp_gt_i32_e64 s[8:9], 0, v0
	v_med3_i32 v0, v0, 0, v184
	v_lshl_add_u32 v0, v0, 2, s91
	ds_read_b32 v0, v0
	s_and_b64 s[8:9], vcc, s[8:9]
	s_waitcnt lgkmcnt(0)
	v_cndmask_b32_e64 v123, v0, v185, s[8:9]
	v_add_u32_e32 v0, 49, v213
	v_cmp_gt_i32_e64 s[8:9], 0, v0
	v_med3_i32 v0, v0, 0, v184
	v_lshl_add_u32 v0, v0, 2, s91
	ds_read_b32 v0, v0
	s_and_b64 s[8:9], vcc, s[8:9]
	s_waitcnt lgkmcnt(0)
	v_cndmask_b32_e64 v124, v0, v185, s[8:9]
	v_add_u32_e32 v0, 48, v213
	v_cmp_gt_i32_e64 s[8:9], 0, v0
	v_med3_i32 v0, v0, 0, v184
	v_lshl_add_u32 v0, v0, 2, s91
	ds_read_b32 v0, v0
	s_and_b64 s[8:9], vcc, s[8:9]
	s_waitcnt lgkmcnt(0)
	v_cndmask_b32_e64 v125, v0, v185, s[8:9]
	v_add_u32_e32 v0, 35, v213
	v_cmp_gt_i32_e64 s[8:9], 0, v0
	v_med3_i32 v0, v0, 0, v184
	v_lshl_add_u32 v0, v0, 2, s91
	ds_read_b32 v0, v0
	s_and_b64 s[8:9], vcc, s[8:9]
	s_waitcnt lgkmcnt(0)
	v_cndmask_b32_e64 v126, v0, v185, s[8:9]
	v_add_u32_e32 v0, 34, v213
	v_cmp_gt_i32_e64 s[8:9], 0, v0
	v_med3_i32 v0, v0, 0, v184
	v_lshl_add_u32 v0, v0, 2, s91
	ds_read_b32 v0, v0
	s_and_b64 s[8:9], vcc, s[8:9]
	s_waitcnt lgkmcnt(0)
	v_cndmask_b32_e64 v127, v0, v185, s[8:9]
	v_add_u32_e32 v0, 33, v213
	v_cmp_gt_i32_e64 s[8:9], 0, v0
	v_med3_i32 v0, v0, 0, v184
	v_lshl_add_u32 v0, v0, 2, s91
	ds_read_b32 v0, v0
	s_and_b64 s[8:9], vcc, s[8:9]
	s_waitcnt lgkmcnt(0)
	v_cndmask_b32_e64 v128, v0, v185, s[8:9]
	v_add_u32_e32 v0, 32, v213
	v_cmp_gt_i32_e64 s[8:9], 0, v0
	v_med3_i32 v0, v0, 0, v184
	v_lshl_add_u32 v0, v0, 2, s91
	ds_read_b32 v0, v0
	s_and_b64 s[8:9], vcc, s[8:9]
	s_waitcnt lgkmcnt(0)
	v_cndmask_b32_e64 v129, v0, v185, s[8:9]
	v_add_u32_e32 v0, 19, v213
	v_cmp_gt_i32_e64 s[8:9], 0, v0
	v_med3_i32 v0, v0, 0, v184
	v_lshl_add_u32 v0, v0, 2, s91
	ds_read_b32 v0, v0
	s_and_b64 s[8:9], vcc, s[8:9]
	s_waitcnt lgkmcnt(0)
	v_cndmask_b32_e64 v130, v0, v185, s[8:9]
	v_add_u32_e32 v0, 18, v213
	v_cmp_gt_i32_e64 s[8:9], 0, v0
	v_med3_i32 v0, v0, 0, v184
	v_lshl_add_u32 v0, v0, 2, s91
	ds_read_b32 v0, v0
	s_and_b64 s[8:9], vcc, s[8:9]
	s_waitcnt lgkmcnt(0)
	v_cndmask_b32_e64 v131, v0, v185, s[8:9]
	v_add_u32_e32 v0, 17, v213
	v_cmp_gt_i32_e64 s[8:9], 0, v0
	v_med3_i32 v0, v0, 0, v184
	v_lshl_add_u32 v0, v0, 2, s91
	ds_read_b32 v0, v0
	s_and_b64 s[8:9], vcc, s[8:9]
	s_waitcnt lgkmcnt(0)
	v_cndmask_b32_e64 v132, v0, v185, s[8:9]
	v_add_u32_e32 v0, 16, v213
	v_cmp_gt_i32_e64 s[8:9], 0, v0
	v_med3_i32 v0, v0, 0, v184
	v_lshl_add_u32 v0, v0, 2, s91
	ds_read_b32 v0, v0
	s_and_b64 s[8:9], vcc, s[8:9]
	s_waitcnt lgkmcnt(0)
	v_cndmask_b32_e64 v133, v0, v185, s[8:9]
	v_add_u32_e32 v0, 3, v213
	v_cmp_gt_i32_e64 s[8:9], 0, v0
	v_med3_i32 v0, v0, 0, v184
	v_lshl_add_u32 v0, v0, 2, s91
	ds_read_b32 v0, v0
	s_and_b64 s[8:9], vcc, s[8:9]
	s_waitcnt lgkmcnt(0)
	v_cndmask_b32_e64 v142, v0, v185, s[8:9]
	v_add_u32_e32 v0, 2, v213
	v_cmp_gt_i32_e64 s[8:9], 0, v0
	v_med3_i32 v0, v0, 0, v184
	v_lshl_add_u32 v0, v0, 2, s91
	ds_read_b32 v0, v0
	s_and_b64 s[8:9], vcc, s[8:9]
	s_waitcnt lgkmcnt(0)
	v_cndmask_b32_e64 v143, v0, v185, s[8:9]
	v_add_u32_e32 v0, 1, v213
	v_cmp_gt_i32_e64 s[8:9], 0, v0
	v_med3_i32 v0, v0, 0, v184
	v_lshl_add_u32 v0, v0, 2, s91
	ds_read_b32 v0, v0
	s_and_b64 s[8:9], vcc, s[8:9]
	s_waitcnt lgkmcnt(0)
	v_cndmask_b32_e64 v144, v0, v185, s[8:9]
	v_med3_i32 v0, v213, 0, v184
	v_lshl_add_u32 v0, v0, 2, s91
	ds_read_b32 v0, v0
	v_cmp_gt_i32_e64 s[8:9], 0, v213
	s_and_b64 vcc, vcc, s[8:9]
	s_waitcnt lgkmcnt(0)
	v_cndmask_b32_e32 v145, v0, v185, vcc

; template <int NC, int DQK, int DV, bool CAUSAL, bool PF> ...
;     ...
;     _Pragma("unroll") for (int c = 0; c < NC; ++c) {
;       f32x4 s[4];
;       _Pragma("unroll") for (int m = 0; m < 4; ++m) s[m] = f32x4{0.f, 0.f, 0.f, 0.f};
;       _Pragma("unroll") for (int ks = 0; ks < NKS; ++ks) _Pragma("unroll") for (int m = 0; m < 4; ++m) {
;         bf16x8 a = *(const bf16x8*)&Kb[(16 * m + fr) * KLD + c * DQK + ks * 32 + fq * 8];
;         s[m] = __builtin_amdgcn_mfma_f32_16x16x32_bf16(a, qf[c][ks], s[m], 0, 0, 0);
;       }
;       constexpr float THR = 8.f;
;       float tnew, psum = 0.f;
;       if (general) {
;         float tmax = -1e30f;
;         _Pragma("unroll") for (int m = 0; m < 4; ++m) _Pragma("unroll") for (int j = 0; j < 4; ++j) {
;           float v = s[m][j] * scale_log2 + bv[m][j];
;           s[m][j] = v; tmax = fmaxf(tmax, v);
;         }
;         tnew = tmax;
;       } else {
;         float rmax = fmaxf(fmaxf(s[0][0], s[0][1]), fmaxf(s[0][2], s[0][3]));
;         _Pragma("unroll") for (int m = 1; m < 4; ++m) rmax = fmaxf(rmax, fmaxf(fmaxf(s[m][0], s[m][1]), fmaxf(s[m][2], s[m][3])));
;         tnew = rmax * scale_log2 + bb;
;       }
;       if (__builtin_amdgcn_ballot_w64(tnew - mrun[c] > THR) != 0ull) {
;         tnew = fmaxf(tnew, sx<16>(tnew, lane)); tnew = fmaxf(tnew, sx<32>(tnew, lane));
;         float mnew = fmaxf(mrun[c], tnew);
;         float alpha = __builtin_amdgcn_exp2f(mrun[c] - mnew);
;         mrun[c] = mnew; lsum[c] *= alpha;
;         _Pragma("unroll") for (int v = 0; v < NVT; ++v) _Pragma("unroll") for (int j = 0; j < 4; ++j) O[c][v][j] *= alpha;
;       }
;       if (general) {
;         float mm = mrun[c];
;         _Pragma("unroll") for (int m = 0; m < 4; ++m) _Pragma("unroll") for (int j = 0; j < 4; ++j) { float pv = __builtin_amdgcn_exp2f(s[m][j] - mm); s[m][j] = pv; psum += pv; }
;       } else {
;         float cc = bb - mrun[c];
;         _Pragma("unroll") for (int m = 0; m < 4; ++m) _Pragma("unroll") for (int j = 0; j < 4; ++j) { float pv = __builtin_amdgcn_exp2f(s[m][j] * scale_log2 + cc); s[m][j] = pv; psum += pv; }
;       }
;       lsum[c] += psum;
.Lda_fast:
	v_add3_u32 v172, s38, v32, v195
	v_add3_u32 v173, s37, v32, v193
	ds_read_b128 v[146:149], v172
	ds_read_b128 v[150:153], v172 offset:4352
	ds_read_b128 v[154:157], v172 offset:8704
	ds_read_b128 v[158:161], v172 offset:13056
	ds_read_b128 v[16:19], v172 offset:64
	ds_read_b128 v[20:23], v172 offset:4416
	ds_read_b128 v[24:27], v172 offset:8768
	ds_read_b128 v[28:31], v172 offset:13120
	ds_read_b128 v[0:3], v172 offset:128
	ds_read_b128 v[4:7], v172 offset:4480
	ds_read_b128 v[8:11], v172 offset:8832
	ds_read_b128 v[12:15], v172 offset:13184
	s_waitcnt lgkmcnt(11)
	v_mfma_f32_16x16x32_bf16 v[146:149], v[146:149], v[138:141], 0
	s_waitcnt lgkmcnt(10)
	v_mfma_f32_16x16x32_bf16 v[150:153], v[150:153], v[138:141], 0
	s_waitcnt lgkmcnt(9)
	v_mfma_f32_16x16x32_bf16 v[154:157], v[154:157], v[138:141], 0
	s_waitcnt lgkmcnt(8)
	v_mfma_f32_16x16x32_bf16 v[158:161], v[158:161], v[138:141], 0
	s_waitcnt lgkmcnt(7)
	v_mfma_f32_16x16x32_bf16 v[146:149], v[16:19], v[134:137], v[146:149]
	s_waitcnt lgkmcnt(6)
	v_mfma_f32_16x16x32_bf16 v[150:153], v[20:23], v[134:137], v[150:153]
	s_waitcnt lgkmcnt(5)
	v_mfma_f32_16x16x32_bf16 v[154:157], v[24:27], v[134:137], v[154:157]
	s_waitcnt lgkmcnt(4)
	v_mfma_f32_16x16x32_bf16 v[158:161], v[28:31], v[134:137], v[158:161]
	ds_read_b128 v[16:19], v172 offset:192
	ds_read_b128 v[20:23], v172 offset:4544
	ds_read_b128 v[24:27], v172 offset:8896
	ds_read_b128 v[28:31], v172 offset:13248
	ds_read_b128 v[122:125], v173 offset:34816
	ds_read_b128 v[126:129], v173 offset:37120
	ds_read_b128 v[130:133], v173 offset:39424
	ds_read_b128 v[142:145], v173 offset:41728
	s_waitcnt lgkmcnt(11)
	v_mfma_f32_16x16x32_bf16 v[0:3], v[0:3], v[118:121], 0
	s_waitcnt lgkmcnt(10)
	v_mfma_f32_16x16x32_bf16 v[4:7], v[4:7], v[118:121], 0
	s_waitcnt lgkmcnt(9)
	v_mfma_f32_16x16x32_bf16 v[8:11], v[8:11], v[118:121], 0
	s_waitcnt lgkmcnt(8)
	v_mfma_f32_16x16x32_bf16 v[12:15], v[12:15], v[118:121], 0
	v_max3_f32 v174, v146, v147, v148
	v_max3_f32 v175, v149, v150, v151
	v_max3_f32 v174, v174, v152, v153
	v_max3_f32 v175, v175, v154, v155
	v_max3_f32 v174, v174, v156, v157
	v_max3_f32 v175, v175, v158, v159
	v_max3_f32 v174, v174, v160, v161
	v_max_f32_e32 v174, v174, v175
	v_fmamk_f32 v174, v174, 0x3e38aa3b, v170
	v_sub_f32_e32 v175, v174, v194
	v_cmp_lt_f32_e32 vcc, s33, v175
	s_cbranch_vccnz .Lda_resc0
.Lda_resc0_ret:
	v_sub_f32_e32 v175, v170, v194
	s_waitcnt lgkmcnt(7)
	v_mfma_f32_16x16x32_bf16 v[0:3], v[16:19], v[114:117], v[0:3]
	s_waitcnt lgkmcnt(6)
	v_mfma_f32_16x16x32_bf16 v[4:7], v[20:23], v[114:117], v[4:7]
	s_waitcnt lgkmcnt(5)
	v_mfma_f32_16x16x32_bf16 v[8:11], v[24:27], v[114:117], v[8:11]
	s_waitcnt lgkmcnt(4)
	v_mfma_f32_16x16x32_bf16 v[12:15], v[28:31], v[114:117], v[12:15]
	ds_read_b128 v[16:19], v173 offset:44032
	ds_read_b128 v[20:23], v173 offset:46336
	ds_read_b128 v[24:27], v173 offset:48640
	ds_read_b128 v[28:31], v173 offset:50944
	v_fmamk_f32 v146, v146, 0x3e38aa3b, v175
	v_fmamk_f32 v147, v147, 0x3e38aa3b, v175
	v_fmamk_f32 v148, v148, 0x3e38aa3b, v175
	v_fmamk_f32 v149, v149, 0x3e38aa3b, v175
	v_fmamk_f32 v150, v150, 0x3e38aa3b, v175
	v_fmamk_f32 v151, v151, 0x3e38aa3b, v175
	v_fmamk_f32 v152, v152, 0x3e38aa3b, v175
	v_fmamk_f32 v153, v153, 0x3e38aa3b, v175
	v_fmamk_f32 v154, v154, 0x3e38aa3b, v175
	v_fmamk_f32 v155, v155, 0x3e38aa3b, v175
	v_fmamk_f32 v156, v156, 0x3e38aa3b, v175
	v_fmamk_f32 v157, v157, 0x3e38aa3b, v175
	v_fmamk_f32 v158, v158, 0x3e38aa3b, v175
	v_fmamk_f32 v159, v159, 0x3e38aa3b, v175
	v_fmamk_f32 v160, v160, 0x3e38aa3b, v175
	v_fmamk_f32 v161, v161, 0x3e38aa3b, v175
	v_exp_f32_e32 v146, v146
	v_exp_f32_e32 v147, v147
	v_exp_f32_e32 v148, v148
	v_add_f32_e32 v174, v147, v146
	v_exp_f32_e32 v149, v149
	v_add_f32_e32 v174, v148, v174
	v_exp_f32_e32 v150, v150
	v_add_f32_e32 v174, v149, v174
	v_exp_f32_e32 v151, v151
	v_add_f32_e32 v174, v150, v174
	v_exp_f32_e32 v152, v152
	v_add_f32_e32 v174, v151, v174
	v_exp_f32_e32 v153, v153
	v_add_f32_e32 v174, v152, v174
	v_exp_f32_e32 v154, v154
	v_add_f32_e32 v174, v153, v174
	v_exp_f32_e32 v155, v155
	v_add_f32_e32 v174, v154, v174
	v_exp_f32_e32 v156, v156
	v_add_f32_e32 v174, v155, v174
	v_exp_f32_e32 v157, v157
	v_add_f32_e32 v174, v156, v174
	v_exp_f32_e32 v158, v158
	v_add_f32_e32 v174, v157, v174
	v_exp_f32_e32 v159, v159
	v_add_f32_e32 v174, v158, v174
	v_exp_f32_e32 v160, v160
	v_add_f32_e32 v174, v159, v174
	v_exp_f32_e32 v161, v161
	v_add_f32_e32 v174, v160, v174
	v_cvt_pk_bf16_f32 v146, v146, v147
	v_add_f32_e32 v174, v161, v174
	v_cvt_pk_bf16_f32 v147, v148, v149
	v_add_f32_e32 v192, v192, v174
	v_cvt_pk_bf16_f32 v148, v150, v151
	v_cvt_pk_bf16_f32 v149, v152, v153
	v_cvt_pk_bf16_f32 v150, v154, v155
	v_cvt_pk_bf16_f32 v151, v156, v157
	v_cvt_pk_bf16_f32 v152, v158, v159
	v_cvt_pk_bf16_f32 v153, v160, v161
	ds_read_b128 v[154:157], v173 offset:34880
	ds_read_b128 v[158:161], v173 offset:37184
	v_max3_f32 v174, v0, v1, v2
	v_max3_f32 v175, v3, v4, v5
	v_max3_f32 v174, v174, v6, v7
	v_max3_f32 v175, v175, v8, v9
	v_max3_f32 v174, v174, v10, v11
	v_max3_f32 v175, v175, v12, v13
	v_max3_f32 v174, v174, v14, v15
	v_max_f32_e32 v174, v174, v175
	v_fmamk_f32 v174, v174, 0x3e38aa3b, v170
	v_sub_f32_e32 v175, v174, v171
	v_cmp_lt_f32_e32 vcc, s33, v175
	s_cbranch_vccnz .Lda_resc1
; __device__ __forceinline__ uint2 pack4(float a, float b, float c, float d) { uint2 r; r.x = pk2(a, b); r.y = pk2(c, d); return r; }
; template <int NC, int DQK, int DV, bool CAUSAL, bool PF> ...
;     ...
;         _Pragma("unroll") for (int m = 0; m < 4; ++m) _Pragma("unroll") for (int j = 0; j < 4; ++j) { float pv = __builtin_amdgcn_exp2f(s[m][j] - mm); s[m][j] = pv; psum += pv; }
;       } else {
;         float cc = bb - mrun[c];
;         _Pragma("unroll") for (int m = 0; m < 4; ++m) _Pragma("unroll") for (int j = 0; j < 4; ++j) { float pv = __builtin_amdgcn_exp2f(s[m][j] * scale_log2 + cc); s[m][j] = pv; psum += pv; }
;       }
;       lsum[c] += psum;
;       _Pragma("unroll") for (int k2 = 0; k2 < 2; ++k2) {
;         uint2 lo = pack4(s[2 * k2][0], s[2 * k2][1], s[2 * k2][2], s[2 * k2][3]);
;         uint2 hi = pack4(s[2 * k2 + 1][0], s[2 * k2 + 1][1], s[2 * k2 + 1][2], s[2 * k2 + 1][3]);
;         uint4 pk; pk.x = lo.x; pk.y = lo.y; pk.z = hi.x; pk.w = hi.y;
;         pf[c][k2] = *(bf16x8*)&pk;
;       }
;     }
;     _Pragma("unroll") for (int k2 = 0; k2 < 2; ++k2) _Pragma("unroll") for (int v = 0; v < NVT; ++v) {
;       bf16x8 a = *(const bf16x8*)&Vb[(16 * v + fr) * VLD + 32 * k2 + fq * 8];
;       _Pragma("unroll") for (int c = 0; c < NC; ++c) O[c][v] = __builtin_amdgcn_mfma_f32_16x16x32_bf16(a, pf[c][k2], O[c][v], 0, 0, 0);
;       if ((v & 3) == 3) __builtin_amdgcn_sched_barrier(0);
;     }
.Lda_resc1_ret:
	v_sub_f32_e32 v175, v170, v171
	v_fmamk_f32 v0, v0, 0x3e38aa3b, v175
	v_fmamk_f32 v1, v1, 0x3e38aa3b, v175
	v_fmamk_f32 v2, v2, 0x3e38aa3b, v175
	v_fmamk_f32 v3, v3, 0x3e38aa3b, v175
	v_fmamk_f32 v4, v4, 0x3e38aa3b, v175
	v_fmamk_f32 v5, v5, 0x3e38aa3b, v175
	v_fmamk_f32 v6, v6, 0x3e38aa3b, v175
	v_fmamk_f32 v7, v7, 0x3e38aa3b, v175
	v_fmamk_f32 v8, v8, 0x3e38aa3b, v175
	v_fmamk_f32 v9, v9, 0x3e38aa3b, v175
	v_fmamk_f32 v10, v10, 0x3e38aa3b, v175
	v_fmamk_f32 v11, v11, 0x3e38aa3b, v175
	v_fmamk_f32 v12, v12, 0x3e38aa3b, v175
	v_fmamk_f32 v13, v13, 0x3e38aa3b, v175
	v_fmamk_f32 v14, v14, 0x3e38aa3b, v175
	v_fmamk_f32 v15, v15, 0x3e38aa3b, v175
	v_exp_f32_e32 v0, v0
	v_exp_f32_e32 v1, v1
	v_exp_f32_e32 v2, v2
	v_add_f32_e32 v174, v1, v0
	v_exp_f32_e32 v3, v3
	v_add_f32_e32 v174, v2, v174
	v_exp_f32_e32 v4, v4
	v_add_f32_e32 v174, v3, v174
	v_exp_f32_e32 v5, v5
	v_add_f32_e32 v174, v4, v174
	v_exp_f32_e32 v6, v6
	v_add_f32_e32 v174, v5, v174
	v_exp_f32_e32 v7, v7
	v_add_f32_e32 v174, v6, v174
	v_exp_f32_e32 v8, v8
	v_add_f32_e32 v174, v7, v174
	v_exp_f32_e32 v9, v9
	v_add_f32_e32 v174, v8, v174
	v_exp_f32_e32 v10, v10
	v_add_f32_e32 v174, v9, v174
	v_exp_f32_e32 v11, v11
	v_add_f32_e32 v174, v10, v174
	v_exp_f32_e32 v12, v12
	v_add_f32_e32 v174, v11, v174
	v_exp_f32_e32 v13, v13
	v_add_f32_e32 v174, v12, v174
	v_exp_f32_e32 v14, v14
	v_add_f32_e32 v174, v13, v174
	v_exp_f32_e32 v15, v15
	v_add_f32_e32 v174, v14, v174
	v_cvt_pk_bf16_f32 v0, v0, v1
	v_add_f32_e32 v174, v15, v174
	v_cvt_pk_bf16_f32 v1, v2, v3
	v_add_f32_e32 v191, v191, v174
	v_cvt_pk_bf16_f32 v2, v4, v5
	v_cvt_pk_bf16_f32 v3, v6, v7
	v_cvt_pk_bf16_f32 v4, v8, v9
	v_cvt_pk_bf16_f32 v5, v10, v11
	v_cvt_pk_bf16_f32 v6, v12, v13
	v_cvt_pk_bf16_f32 v7, v14, v15
	ds_read_b128 v[8:11], v173 offset:39488
	ds_read_b128 v[12:15], v173 offset:41792
	s_waitcnt lgkmcnt(11)
	v_mfma_f32_16x16x32_bf16 v[106:109], v[122:125], v[146:149], v[106:109]
	v_mfma_f32_16x16x32_bf16 v[110:113], v[122:125], v[0:3], v[110:113]
	s_waitcnt lgkmcnt(10)
	v_mfma_f32_16x16x32_bf16 v[98:101], v[126:129], v[146:149], v[98:101]
	v_mfma_f32_16x16x32_bf16 v[102:105], v[126:129], v[0:3], v[102:105]
	s_waitcnt lgkmcnt(9)
	v_mfma_f32_16x16x32_bf16 v[90:93], v[130:133], v[146:149], v[90:93]
	v_mfma_f32_16x16x32_bf16 v[94:97], v[130:133], v[0:3], v[94:97]
	s_waitcnt lgkmcnt(8)
	v_mfma_f32_16x16x32_bf16 v[78:81], v[142:145], v[146:149], v[78:81]
	v_mfma_f32_16x16x32_bf16 v[74:77], v[142:145], v[0:3], v[74:77]
	ds_read_b128 v[122:125], v173 offset:44096
	ds_read_b128 v[126:129], v173 offset:46400
	ds_read_b128 v[130:133], v173 offset:48704
	ds_read_b128 v[142:145], v173 offset:51008
	s_waitcnt lgkmcnt(11)
	v_mfma_f32_16x16x32_bf16 v[62:65], v[16:19], v[146:149], v[62:65]
	v_mfma_f32_16x16x32_bf16 v[70:73], v[16:19], v[0:3], v[70:73]
	s_waitcnt lgkmcnt(10)
	v_mfma_f32_16x16x32_bf16 v[50:53], v[20:23], v[146:149], v[50:53]
	v_mfma_f32_16x16x32_bf16 v[66:69], v[20:23], v[0:3], v[66:69]
	s_waitcnt lgkmcnt(9)
	v_mfma_f32_16x16x32_bf16 v[54:57], v[24:27], v[146:149], v[54:57]
	v_mfma_f32_16x16x32_bf16 v[58:61], v[24:27], v[0:3], v[58:61]
	s_waitcnt lgkmcnt(8)
	v_mfma_f32_16x16x32_bf16 v[82:85], v[28:31], v[146:149], v[82:85]
	v_mfma_f32_16x16x32_bf16 v[86:89], v[28:31], v[0:3], v[86:89]
	s_waitcnt lgkmcnt(7)
	v_mfma_f32_16x16x32_bf16 v[106:109], v[154:157], v[150:153], v[106:109]
	v_mfma_f32_16x16x32_bf16 v[110:113], v[154:157], v[4:7], v[110:113]
	s_waitcnt lgkmcnt(6)
	v_mfma_f32_16x16x32_bf16 v[98:101], v[158:161], v[150:153], v[98:101]
	v_mfma_f32_16x16x32_bf16 v[102:105], v[158:161], v[4:7], v[102:105]
	s_waitcnt lgkmcnt(5)
	v_mfma_f32_16x16x32_bf16 v[90:93], v[8:11], v[150:153], v[90:93]
	v_mfma_f32_16x16x32_bf16 v[94:97], v[8:11], v[4:7], v[94:97]
	s_waitcnt lgkmcnt(4)
	v_mfma_f32_16x16x32_bf16 v[78:81], v[12:15], v[150:153], v[78:81]
	v_mfma_f32_16x16x32_bf16 v[74:77], v[12:15], v[4:7], v[74:77]
	s_waitcnt lgkmcnt(3)
	v_mfma_f32_16x16x32_bf16 v[62:65], v[122:125], v[150:153], v[62:65]
	v_mfma_f32_16x16x32_bf16 v[70:73], v[122:125], v[4:7], v[70:73]
	s_waitcnt lgkmcnt(2)
	v_mfma_f32_16x16x32_bf16 v[50:53], v[126:129], v[150:153], v[50:53]
	v_mfma_f32_16x16x32_bf16 v[66:69], v[126:129], v[4:7], v[66:69]
	s_waitcnt lgkmcnt(1)
	v_mfma_f32_16x16x32_bf16 v[54:57], v[130:133], v[150:153], v[54:57]
	v_mfma_f32_16x16x32_bf16 v[58:61], v[130:133], v[4:7], v[58:61]
	s_waitcnt lgkmcnt(0)
	v_mfma_f32_16x16x32_bf16 v[82:85], v[142:145], v[150:153], v[82:85]
	v_mfma_f32_16x16x32_bf16 v[86:89], v[142:145], v[4:7], v[86:89]
	s_branch .LBB0_1784
; template <int NC, int DQK, int DV, bool CAUSAL, bool PF> ...
;     ...
;       if (__builtin_amdgcn_ballot_w64(tnew - mrun[c] > THR) != 0ull) {
;         tnew = fmaxf(tnew, sx<16>(tnew, lane)); tnew = fmaxf(tnew, sx<32>(tnew, lane));
;         float mnew = fmaxf(mrun[c], tnew);
;         float alpha = __builtin_amdgcn_exp2f(mrun[c] - mnew);
;         mrun[c] = mnew; lsum[c] *= alpha;
;         _Pragma("unroll") for (int v = 0; v < NVT; ++v) _Pragma("unroll") for (int j = 0; j < 4; ++j) O[c][v][j] *= alpha;
;       }
.Lda_resc0:
	ds_swizzle_b32 v175, v174 offset:swizzle(SWAP,16)
	s_waitcnt lgkmcnt(0)
	v_max_f32_e32 v174, v174, v175
	s_nop 0
	ds_bpermute_b32 v175, v189, v174
	s_waitcnt lgkmcnt(0)
	v_max3_f32 v175, v194, v174, v175
	v_sub_f32_e32 v174, v194, v175
	v_exp_f32_e32 v174, v174
	v_mov_b32_e32 v194, v175
	v_mul_f32_e32 v192, v192, v174
	v_pk_mul_f32 v[106:107], v[106:107], v[174:175] op_sel_hi:[1,0]
	v_pk_mul_f32 v[108:109], v[108:109], v[174:175] op_sel_hi:[1,0]
	v_pk_mul_f32 v[98:99], v[98:99], v[174:175] op_sel_hi:[1,0]
	v_pk_mul_f32 v[100:101], v[100:101], v[174:175] op_sel_hi:[1,0]
	v_pk_mul_f32 v[90:91], v[90:91], v[174:175] op_sel_hi:[1,0]
	v_pk_mul_f32 v[92:93], v[92:93], v[174:175] op_sel_hi:[1,0]
	v_pk_mul_f32 v[78:79], v[78:79], v[174:175] op_sel_hi:[1,0]
	v_pk_mul_f32 v[80:81], v[80:81], v[174:175] op_sel_hi:[1,0]
	v_pk_mul_f32 v[62:63], v[62:63], v[174:175] op_sel_hi:[1,0]
	v_pk_mul_f32 v[64:65], v[64:65], v[174:175] op_sel_hi:[1,0]
	v_pk_mul_f32 v[50:51], v[50:51], v[174:175] op_sel_hi:[1,0]
	v_pk_mul_f32 v[52:53], v[52:53], v[174:175] op_sel_hi:[1,0]
	v_pk_mul_f32 v[54:55], v[54:55], v[174:175] op_sel_hi:[1,0]
	v_pk_mul_f32 v[56:57], v[56:57], v[174:175] op_sel_hi:[1,0]
	v_pk_mul_f32 v[82:83], v[82:83], v[174:175] op_sel_hi:[1,0]
	v_pk_mul_f32 v[84:85], v[84:85], v[174:175] op_sel_hi:[1,0]
	s_branch .Lda_resc0_ret
.Lda_resc1:
	ds_swizzle_b32 v175, v174 offset:swizzle(SWAP,16)
	s_waitcnt lgkmcnt(0)
	v_max_f32_e32 v174, v174, v175
	s_nop 0
	ds_bpermute_b32 v175, v189, v174
	s_waitcnt lgkmcnt(0)
	v_max3_f32 v175, v171, v174, v175
	v_sub_f32_e32 v174, v171, v175
	v_exp_f32_e32 v174, v174
	v_mov_b32_e32 v171, v175
	v_mul_f32_e32 v191, v191, v174
	v_pk_mul_f32 v[110:111], v[110:111], v[174:175] op_sel_hi:[1,0]
	v_pk_mul_f32 v[112:113], v[112:113], v[174:175] op_sel_hi:[1,0]
	v_pk_mul_f32 v[102:103], v[102:103], v[174:175] op_sel_hi:[1,0]
	v_pk_mul_f32 v[104:105], v[104:105], v[174:175] op_sel_hi:[1,0]
	v_pk_mul_f32 v[94:95], v[94:95], v[174:175] op_sel_hi:[1,0]
	v_pk_mul_f32 v[96:97], v[96:97], v[174:175] op_sel_hi:[1,0]
	v_pk_mul_f32 v[74:75], v[74:75], v[174:175] op_sel_hi:[1,0]
	v_pk_mul_f32 v[76:77], v[76:77], v[174:175] op_sel_hi:[1,0]
	v_pk_mul_f32 v[70:71], v[70:71], v[174:175] op_sel_hi:[1,0]
	v_pk_mul_f32 v[72:73], v[72:73], v[174:175] op_sel_hi:[1,0]
	v_pk_mul_f32 v[66:67], v[66:67], v[174:175] op_sel_hi:[1,0]
	v_pk_mul_f32 v[68:69], v[68:69], v[174:175] op_sel_hi:[1,0]
	v_pk_mul_f32 v[58:59], v[58:59], v[174:175] op_sel_hi:[1,0]
	v_pk_mul_f32 v[60:61], v[60:61], v[174:175] op_sel_hi:[1,0]
	v_pk_mul_f32 v[86:87], v[86:87], v[174:175] op_sel_hi:[1,0]
	v_pk_mul_f32 v[88:89], v[88:89], v[174:175] op_sel_hi:[1,0]
	s_branch .Lda_resc1_ret
